# P2b LRU carry scan: hoist the 16 loads above the stores, counted vmcnt instead of 8 serialized round trips
# speedup vs baseline: 1.1121x; 1.1121x over previous
.LBB0_528:
	v_and_b32_e32 v8, 0xe000, v6
	s_movk_i32 s5, 0x3ff
	v_and_or_b32 v9, v4, s5, v8
	v_lshlrev_b32_e32 v9, 2, v9
	v_or_b32_e32 v121, 0x1000, v9
	v_or_b32_e32 v122, 0x2000, v9
	v_or_b32_e32 v123, 0x3000, v9
	global_load_dword v100, v9, s[26:27]
	global_load_dword v110, v9, s[28:29]
	global_load_dword v101, v121, s[26:27]
	global_load_dword v111, v121, s[28:29]
	v_or_b32_e32 v124, 0x4000, v9
	global_load_dword v102, v122, s[26:27]
	global_load_dword v112, v122, s[28:29]
	v_or_b32_e32 v125, 0x5000, v9
	global_load_dword v103, v123, s[26:27]
	global_load_dword v113, v123, s[28:29]
	v_or_b32_e32 v126, 0x6000, v9
	global_load_dword v104, v124, s[26:27]
	global_load_dword v114, v124, s[28:29]
	v_or_b32_e32 v127, 0x7000, v9
	global_load_dword v105, v125, s[26:27]
	global_load_dword v115, v125, s[28:29]
	global_load_dword v106, v126, s[26:27]
	global_load_dword v116, v126, s[28:29]
	global_load_dword v107, v127, s[26:27]
	global_load_dword v117, v127, s[28:29]
	global_store_dword v9, v7, s[48:49]
	v_add_u32_e32 v6, s4, v6
	v_lshl_add_u64 v[4:5], v[4:5], 0, s[54:55]
	v_cmp_lt_u64_e32 vcc, s[6:7], v[4:5]
	s_or_b64 s[38:39], vcc, s[38:39]
	s_waitcnt vmcnt(15)
	v_fmac_f32_e32 v110, 0, v100
	global_store_dword v121, v110, s[48:49]
	s_waitcnt vmcnt(14)
	v_fmac_f32_e32 v111, v110, v101
	global_store_dword v122, v111, s[48:49]
	s_waitcnt vmcnt(13)
	v_fmac_f32_e32 v112, v111, v102
	global_store_dword v123, v112, s[48:49]
	s_waitcnt vmcnt(12)
	v_fmac_f32_e32 v113, v112, v103
	global_store_dword v124, v113, s[48:49]
	s_waitcnt vmcnt(11)
	v_fmac_f32_e32 v114, v113, v104
	global_store_dword v125, v114, s[48:49]
	s_waitcnt vmcnt(10)
	v_fmac_f32_e32 v115, v114, v105
	global_store_dword v126, v115, s[48:49]
	s_waitcnt vmcnt(9)
	v_fmac_f32_e32 v116, v115, v106
	global_store_dword v127, v116, s[48:49]
	s_waitcnt vmcnt(8)
	v_fmac_f32_e32 v117, v116, v107
	global_store_dword v[2:3], v117, off
	v_lshl_add_u64 v[2:3], v[2:3], 0, s[30:31]
	s_andn2_b64 exec, exec, s[38:39]
	s_cbranch_execnz .LBB0_528
